# DN chunk: the 16 sc[] scalars of the KK/QK scaling segment are prefetched instead of read one at a time
# baseline (speedup 1.0000x reference)
.LBB0_582:
	v_lshlrev_b32_e32 v0, 4, v109
	v_and_b32_e32 v169, 16, v0
	v_or_b32_e32 v171, v169, v165
	v_mul_u32_u24_e32 v0, 0x88, v171
	v_lshlrev_b32_e32 v0, 1, v0
	v_lshlrev_b32_e32 v170, 1, v152
	v_add3_u32 v172, 16, v0, v170
	v_lshlrev_b32_e32 v0, 4, v168
	v_or_b32_e32 v155, v0, v165
	v_mul_lo_u32 v60, v155, s69
	v_add3_u32 v152, 16, v60, v170
	ds_read_b128 v[60:63], v172
	ds_read_b128 v[64:67], v172 offset:8704
	ds_read_b128 v[156:159], v152 offset:8704
	v_lshl_or_b32 v169, v154, 2, v169
	s_waitcnt lgkmcnt(0)
	v_mfma_f32_16x16x32_bf16 v[64:67], v[64:67], v[156:159], 0
	v_lshl_add_u32 v173, v169, 2, s70
	ds_read_b32 v220, v173 offset:0
	ds_read_b32 v221, v173 offset:256
	ds_read_b32 v222, v173 offset:512
	ds_read_b32 v223, v173 offset:384
	ds_read_b32 v224, v173 offset:4
	ds_read_b32 v225, v173 offset:260
	ds_read_b32 v226, v173 offset:516
	ds_read_b32 v227, v173 offset:388
	v_cmp_lt_i32_e32 vcc, v155, v169
	v_mfma_f32_16x16x32_bf16 v[60:63], v[60:63], v[156:159], 0
	ds_read_b128 v[156:159], v172 offset:64
	ds_read_b128 v[174:177], v172 offset:8768
	ds_read_b128 v[178:181], v152 offset:8768
	s_waitcnt lgkmcnt(0)
	ds_read_b32 v228, v173 offset:8
	ds_read_b32 v229, v173 offset:264
	ds_read_b32 v230, v173 offset:520
	ds_read_b32 v231, v173 offset:392
	ds_read_b32 v232, v173 offset:12
	ds_read_b32 v233, v173 offset:268
	ds_read_b32 v234, v173 offset:524
	ds_read_b32 v235, v173 offset:396
	v_mfma_f32_16x16x32_bf16 v[64:67], v[174:177], v[178:181], v[64:67]
	v_mfma_f32_16x16x32_bf16 v[60:63], v[156:159], v[178:181], v[60:63]
	ds_read_b128 v[156:159], v172 offset:128
	ds_read_b128 v[174:177], v172 offset:8832
	ds_read_b128 v[178:181], v152 offset:8832
	s_waitcnt lgkmcnt(0)
	v_mfma_f32_16x16x32_bf16 v[64:67], v[174:177], v[178:181], v[64:67]
	v_mfma_f32_16x16x32_bf16 v[60:63], v[156:159], v[178:181], v[60:63]
	ds_read_b128 v[156:159], v172 offset:192
	ds_read_b128 v[174:177], v172 offset:8896
	ds_read_b128 v[178:181], v152 offset:8896
	v_lshl_add_u32 v152, v155, 2, s70
	ds_read2st64_b32 v[152:153], v152 offset1:2
	v_mov_b32_e32 v154, v220
	s_waitcnt lgkmcnt(0)
	v_mfma_f32_16x16x32_bf16 v[64:67], v[174:177], v[178:181], v[64:67]
	s_waitcnt lgkmcnt(0)
	v_sub_f32_e32 v154, v154, v152
	v_mul_f32_e32 v154, 0x3fb8aa3b, v154
	v_mfma_f32_16x16x32_bf16 v[60:63], v[156:159], v[178:181], v[60:63]
	v_exp_f32_e32 v156, v154
	v_mov_b32_e32 v154, 0
	v_mov_b32_e32 v157, 0
	s_and_saveexec_b64 s[2:3], vcc
	s_cbranch_execz .LBB0_584
	v_mov_b32_e32 v158, v221
	v_mov_b32_e32 v159, v222
	s_waitcnt lgkmcnt(0)
	v_mul_f32_e32 v157, v158, v159
	v_mul_f32_e32 v157, v153, v157
	v_mul_f32_e32 v157, v156, v157
	v_mul_f32_e32 v157, v64, v157
.LBB0_584:
	s_or_b64 exec, exec, s[2:3]
	s_movk_i32 s2, 0x90
	v_mul_lo_u32 v64, v155, s2
	v_lshlrev_b32_e32 v158, 2, v169
	v_add3_u32 v64, 16, v64, v158
	v_cmp_le_i32_e32 vcc, v155, v169
	v_mov_b32_e32 v180, 0
	ds_write_b32 v64, v157 offset:45056
	s_and_saveexec_b64 s[2:3], vcc
	s_cbranch_execz .LBB0_586
	v_mov_b32_e32 v157, v223
	s_waitcnt lgkmcnt(0)
	v_mul_f32_e32 v157, v153, v157
	v_mul_f32_e32 v156, v156, v157
	v_mul_f32_e32 v60, v60, v156
	v_cvt_pk_bf16_f32 v180, v60, s0
.LBB0_586:
	s_or_b64 exec, exec, s[2:3]
	v_or_b32_e32 v176, 1, v169
	v_lshl_add_u32 v60, v176, 2, 16
	v_add_u32_e32 v156, 0x11880, v60
	v_mov_b32_e32 v60, v224
	s_waitcnt lgkmcnt(0)
	v_sub_f32_e32 v60, v60, v152
	v_mul_f32_e32 v60, 0x3fb8aa3b, v60
	v_exp_f32_e32 v157, v60
	s_and_saveexec_b64 s[2:3], vcc
	s_cbranch_execz .LBB0_588
	v_mov_b32_e32 v158, v225
	v_mov_b32_e32 v159, v226
	s_waitcnt lgkmcnt(0)
	v_mul_f32_e32 v60, v158, v159
	v_mul_f32_e32 v60, v153, v60
	v_mul_f32_e32 v60, v157, v60
	v_mul_f32_e32 v154, v65, v60
.LBB0_588:
	s_or_b64 exec, exec, s[2:3]
	v_cmp_le_i32_e32 vcc, v155, v176
	v_mov_b32_e32 v60, 0
	v_mov_b32_e32 v178, 0
	ds_write_b32 v64, v154 offset:45060
	s_and_saveexec_b64 s[2:3], vcc
	s_cbranch_execz .LBB0_590
	v_mov_b32_e32 v65, v227
	s_waitcnt lgkmcnt(0)
	v_mul_f32_e32 v65, v153, v65
	v_mul_f32_e32 v65, v157, v65
	v_mul_f32_e32 v61, v61, v65
	v_cvt_pk_bf16_f32 v178, v61, s0
.LBB0_590:
	s_or_b64 exec, exec, s[2:3]
	v_or_b32_e32 v175, 2, v169
	v_lshl_add_u32 v61, v175, 2, 16
	v_add_u32_e32 v61, 0x11880, v61
	v_mov_b32_e32 v65, v228
	v_cmp_lt_i32_e32 vcc, v155, v175
	s_waitcnt lgkmcnt(0)
	v_sub_f32_e32 v65, v65, v152
	v_mul_f32_e32 v65, 0x3fb8aa3b, v65
	v_exp_f32_e32 v65, v65
	s_and_saveexec_b64 s[2:3], vcc
	s_cbranch_execz .LBB0_592
	v_mov_b32_e32 v156, v229
	v_mov_b32_e32 v157, v230
	s_waitcnt lgkmcnt(0)
	v_mul_f32_e32 v60, v156, v157
	v_mul_f32_e32 v60, v153, v60
	v_mul_f32_e32 v60, v65, v60
	v_mul_f32_e32 v60, v66, v60
.LBB0_592:
	s_or_b64 exec, exec, s[2:3]
	ds_write_b32 v64, v60 offset:45064
	v_cmp_le_i32_e32 vcc, v155, v175
	v_mov_b32_e32 v60, 0
	v_mov_b32_e32 v179, 0
	s_and_saveexec_b64 s[2:3], vcc
	s_cbranch_execz .LBB0_594
	v_mov_b32_e32 v61, v231
	s_waitcnt lgkmcnt(0)
	v_mul_f32_e32 v61, v153, v61
	v_mul_f32_e32 v61, v65, v61
	v_mul_f32_e32 v61, v62, v61
	v_cvt_pk_bf16_f32 v179, v61, s0
.LBB0_594:
	s_or_b64 exec, exec, s[2:3]
	v_or_b32_e32 v174, 3, v169
	v_lshl_add_u32 v61, v174, 2, 16
	v_add_u32_e32 v61, 0x11880, v61
	v_mov_b32_e32 v62, v232
	v_cmp_lt_i32_e32 vcc, v155, v174
	s_waitcnt lgkmcnt(0)
	v_sub_f32_e32 v62, v62, v152
	v_mul_f32_e32 v62, 0x3fb8aa3b, v62
	v_exp_f32_e32 v62, v62
	s_and_saveexec_b64 s[2:3], vcc
	s_cbranch_execz .LBB0_596
	v_mov_b32_e32 v156, v233
	v_mov_b32_e32 v157, v234
	s_waitcnt lgkmcnt(0)
	v_mul_f32_e32 v60, v156, v157
	v_mul_f32_e32 v60, v153, v60
	v_mul_f32_e32 v60, v62, v60
	v_mul_f32_e32 v60, v67, v60
.LBB0_596:
	s_or_b64 exec, exec, s[2:3]
	v_cmp_le_i32_e32 vcc, v155, v174
	v_mov_b32_e32 v177, 0
	ds_write_b32 v64, v60 offset:45068
	s_and_saveexec_b64 s[2:3], vcc
	s_cbranch_execz .LBB0_598
	v_mov_b32_e32 v60, v235
	s_waitcnt lgkmcnt(0)
	v_mul_f32_e32 v60, v153, v60
	v_mul_f32_e32 v60, v62, v60
	v_mul_f32_e32 v60, v63, v60
	v_cvt_pk_bf16_f32 v177, v60, s0
